# v62 plus P10 in the 64-contiguous-column layout with pipelined residual loads and DPP-merged whole-line stores
# baseline (speedup 1.0000x reference)
.LBB0_740:
	v_readlane_b32 s0, v254, 1
	v_readlane_b32 s1, v254, 2
	s_mov_b64 s[4:5], s[0:1]
	s_cmp_lt_i32 s4, 11
	v_readlane_b32 s2, v254, 3
	v_readlane_b32 s3, v254, 4
	s_cselect_b64 s[0:1], -1, 0
	s_cmp_gt_i32 s5, 10
	s_cselect_b64 s[2:3], -1, 0
	s_and_b64 s[2:3], s[0:1], s[2:3]
	s_andn2_b64 vcc, exec, s[2:3]
	s_cbranch_vccnz .LBB0_765
	s_bfe_u32 s101, s97, 0x10008
	s_lshl_b32 s101, s101, 18
	v_mbcnt_lo_u32_b32 v8, -1, 0
	v_mbcnt_hi_u32_b32 v8, -1, v8
	s_cmpk_gt_i32 s96, 0x7ff
	v_add_u32_e32 v224, s97, v8
	s_nop 0
	v_readfirstlane_b32 s8, v224
	s_cbranch_scc1 .LBB0_765
	s_ashr_i32 s14, s96, 31
	s_lshr_b32 s0, s14, 29
	s_add_i32 s5, s96, s0
	s_and_b32 s0, s5, -8
	s_sub_i32 s6, s96, s0
	s_cmp_gt_i32 s6, -1
	s_cbranch_scc0 .LBB0_744
	s_lshl_b32 s4, s6, 8
	s_cbranch_execz .LBB0_745
	s_branch .LBB0_746

.LBB0_746:
	v_ashrrev_i32_e32 v1, 31, v224
	v_lshrrev_b32_e32 v1, 26, v1
	v_add_u32_e32 v1, v224, v1
	v_ashrrev_i32_e32 v9, 6, v1
	v_bfe_i32 v1, v224, 27, 1
	v_lshlrev_b32_e32 v0, 4, v224
	v_lshrrev_b32_e32 v1, 22, v1
	v_add_u32_e32 v1, v0, v1
	v_and_b32_e32 v1, 0xfffffc00, v1
	v_sub_u32_e32 v1, v0, v1
	v_lshrrev_b32_e32 v2, 4, v1
	v_bitop3_b32 v1, v2, v1, 32 bitop3:0x6c
	v_ashrrev_i32_e32 v3, 31, v1
	v_lshrrev_b32_e32 v3, 26, v3
	v_add_u32_e32 v3, v1, v3
	v_lshlrev_b32_e32 v2, 3, v9
	v_ashrrev_i32_e32 v10, 6, v3
	v_and_b32_e32 v3, 0xc0, v3
	v_and_b32_e32 v2, -16, v2
	v_sub_u32_e32 v1, v1, v3
	v_mov_b32_e32 v3, 1
	v_add_u32_e32 v2, v10, v2
	v_ashrrev_i16_sdwa v1, v3, sext(v1) dst_sel:DWORD dst_unused:UNUSED_PAD src0_sel:DWORD src1_sel:BYTE_0
	s_ashr_i32 s0, s5, 3
	v_lshlrev_b32_e32 v4, 5, v9
	v_bfe_i32 v11, v1, 0, 16
	v_lshlrev_b32_e32 v1, 1, v2
	v_lshrrev_b32_e32 v5, 2, v2
	v_and_b32_e32 v6, 3, v10
	s_mov_b32 s5, 0x7ffe0
	v_and_b32_e32 v4, 32, v4
	v_and_b32_e32 v1, 24, v1
	v_and_b32_e32 v5, 4, v5
	v_and_or_b32 v6, v2, s5, v6
	v_or3_b32 v1, v6, v5, v1
	v_add_lshl_u32 v4, v4, v11, 1
	v_add_u32_e32 v0, 0x2000, v0
	v_lshl_add_u32 v130, v1, 13, v4
	v_add_u32_e32 v130, s101, v130
	v_ashrrev_i32_e32 v1, 31, v0
	v_lshrrev_b32_e32 v1, 22, v1
	v_add_u32_e32 v1, v0, v1
	v_ashrrev_i32_e32 v12, 10, v1
	v_mul_i32_i24_e32 v1, 0x400, v12
	v_sub_u32_e32 v0, v0, v1
	v_lshrrev_b32_e32 v1, 4, v0
	v_bitop3_b32 v0, v1, v0, 32 bitop3:0x6c
	v_lshl_add_u32 v128, v2, 13, v4
	v_ashrrev_i32_e32 v2, 31, v0
	s_add_u32 s33, s94, 0x3c100000
	v_lshrrev_b32_e32 v2, 26, v2
	s_addc_u32 s66, s95, 0
	v_add_u32_e32 v2, v0, v2
	s_add_i32 s0, s4, s0
	v_lshlrev_b32_e32 v1, 3, v12
	v_ashrrev_i32_e32 v13, 6, v2
	v_and_b32_e32 v2, 0xc0, v2
	s_ashr_i32 s4, s0, 31
	v_and_b32_e32 v1, -16, v1
	v_sub_u32_e32 v0, v0, v2
	s_lshr_b32 s4, s4, 25
	v_add_u32_e32 v1, v13, v1
	v_ashrrev_i16_sdwa v0, v3, sext(v0) dst_sel:DWORD dst_unused:UNUSED_PAD src0_sel:DWORD src1_sel:BYTE_0
	v_and_b32_e32 v3, 3, v13
	s_add_i32 s4, s0, s4
	v_and_or_b32 v3, v1, s5, v3
	s_ashr_i32 s5, s4, 7
	s_and_b32 s4, s4, 0xffffff80
	s_sub_i32 s4, s0, s4
	s_bfe_i32 s0, s4, 0x80000
	s_bfe_u32 s0, s0, 0x3000c
	s_add_i32 s7, s4, s0
	s_bfe_i32 s0, s7, 0x80000
	s_and_b32 s7, s7, 0xf8
	s_sub_i32 s4, s4, s7
	s_lshl_b32 s5, s5, 3
	s_sext_i32_i16 s0, s0
	s_sext_i32_i8 s4, s4
	s_ashr_i32 s1, s8, 8
	s_lshr_b32 s0, s0, 3
	s_add_i32 s44, s5, s4
	s_ashr_i32 s6, s8, 6
	s_ashr_i32 s45, s44, 31
	s_bfe_i64 s[10:11], s[0:1], 0x100000
	s_lshl_b32 s67, s6, 10
	s_lshl_b64 s[4:5], s[44:45], 21
	s_lshl_b64 s[10:11], s[10:11], 21
	s_add_u32 s46, s91, s10
	v_lshlrev_b32_e32 v4, 5, v12
	v_bfe_i32 v14, v0, 0, 16
	v_lshlrev_b32_e32 v0, 1, v1
	v_lshrrev_b32_e32 v2, 2, v1
	s_addc_u32 s47, s85, s11
	s_add_i32 s76, s67, 0
	v_and_b32_e32 v4, 32, v4
	v_and_b32_e32 v0, 24, v0
	v_and_b32_e32 v2, 4, v2
	s_add_i32 m0, s76, 0x10000
	v_or3_b32 v0, v3, v2, v0
	v_add_lshl_u32 v2, v4, v14, 1
	global_load_lds_dwordx4 v130, s[46:47]
	s_add_i32 m0, s76, 0x12000
	v_lshl_add_u32 v134, v0, 13, v2
	v_add_u32_e32 v134, s101, v134
	v_add_u32_e32 v134, 0x80000, v134
	s_add_u32 s10, s46, 0x40000
	global_load_lds_dwordx4 v134, s[46:47]
	s_addc_u32 s11, s47, 0
	s_add_i32 m0, s76, 0x14000
	v_lshl_add_u32 v132, v1, 13, v2
	global_load_lds_dwordx4 v130, s[10:11]
	s_add_i32 m0, s76, 0x16000
	s_add_u32 s48, s33, s4
	s_addc_u32 s49, s66, s5
	s_add_i32 s52, s76, 0x2000
	global_load_lds_dwordx4 v134, s[10:11]
	s_mov_b32 m0, s76
	s_add_u32 s4, s48, 0x100000
	global_load_lds_dwordx4 v128, s[48:49]
	s_mov_b32 m0, s52
	s_addc_u32 s5, s49, 0
	s_add_i32 s53, s76, 0x4000
	global_load_lds_dwordx4 v132, s[48:49]
	s_mov_b32 m0, s53
	s_add_i32 s54, s76, 0x6000
	global_load_lds_dwordx4 v128, s[4:5]
	s_mov_b32 m0, s54
	v_mov_b32_e32 v131, 0
	global_load_lds_dwordx4 v132, s[4:5]
	v_mov_b32_e32 v135, v131
	v_mov_b32_e32 v129, v131
	v_mov_b32_e32 v133, v131
	s_cmp_eq_u32 s1, 1
	s_mov_b32 s55, 0
	v_lshl_add_u64 v[6:7], s[46:47], 0, v[130:131]
	v_lshl_add_u64 v[4:5], s[46:47], 0, v[134:135]
	v_lshl_add_u64 v[0:1], s[48:49], 0, v[128:129]
	s_cselect_b64 s[4:5], -1, 0
	s_cmp_lg_u32 s1, 1
	v_lshl_add_u64 v[2:3], s[48:49], 0, v[132:133]
	s_cbranch_scc1 .LBB0_748
	s_barrier
.LBB0_748:
	s_lshl_b32 s6, s6, 5
	s_and_b32 s12, s6, 0x60
	s_mov_b64 s[6:7], 0x80
	s_add_i32 m0, s76, 0x18000
	v_lshl_add_u64 v[6:7], v[6:7], 0, s[6:7]
	s_lshl_b32 s9, s1, 13
	s_lshl_b32 s13, s12, 7
	s_waitcnt vmcnt(2)
	s_barrier
	global_load_lds_dwordx4 v[6:7], off
	v_lshl_add_u64 v[4:5], v[4:5], 0, s[6:7]
	s_add_i32 m0, s76, 0x1a000
	s_add_i32 s56, s76, 0x8000
	s_add_i32 s57, s76, 0xa000
	global_load_lds_dwordx4 v[4:5], off
	v_lshl_add_u64 v[0:1], v[0:1], 0, s[6:7]
	s_mov_b32 m0, s56
	s_add_u32 s10, s46, 0x40080
	global_load_lds_dwordx4 v[0:1], off
	v_lshl_add_u64 v[0:1], v[2:3], 0, s[6:7]
	s_mov_b32 m0, s57
	s_addc_u32 s11, s47, 0
	global_load_lds_dwordx4 v[0:1], off
	s_add_i32 m0, s76, 0x1c000
	v_lshl_add_u64 v[0:1], s[10:11], 0, v[130:131]
	global_load_lds_dwordx4 v[0:1], off
	v_lshl_add_u64 v[0:1], s[10:11], 0, v[134:135]
	s_add_i32 m0, s76, 0x1e000
	s_cmpk_lt_u32 s8, 0x100
	global_load_lds_dwordx4 v[0:1], off
	v_lshrrev_b32_e32 v1, 1, v8
	v_and_b32_e32 v1, 24, v1
	v_and_b32_e32 v0, 15, v8
	v_lshlrev_b32_e32 v2, 1, v1
	v_lshl_or_b32 v150, s1, 6, v0
	v_lshl_or_b32 v0, v0, 6, v2
	v_lshlrev_b32_e32 v2, 2, v8
	v_and_b32_e32 v2, 32, v2
	v_bitop3_b32 v3, v0, s9, v2 bitop3:0xde
	v_bitop3_b32 v151, s13, v0, v2 bitop3:0xf6
	v_lshlrev_b32_e32 v0, 16, v9
	v_and_b32_e32 v0, 0xfffe0000, v0
	v_or_b32_e32 v152, s12, v1
	v_lshl_add_u32 v0, v10, 13, v0
	v_and_b32_e32 v1, 1, v9
	v_lshl_or_b32 v0, v1, 6, v0
	v_readlane_b32 s16, v254, 7
	v_lshl_add_u32 v136, v11, 1, v0
	v_lshlrev_b32_e32 v0, 16, v12
	s_cselect_b64 s[8:9], -1, 0
	s_ashr_i32 s58, s15, 31
	v_readlane_b32 s18, v254, 9
	v_and_b32_e32 v0, 0xfffe0000, v0
	s_waitcnt vmcnt(6)
	v_readlane_b32 s19, v254, 10
	s_add_u32 s59, s18, 0xf0000000
	v_lshl_add_u32 v0, v13, 13, v0
	v_and_b32_e32 v1, 1, v12
	s_addc_u32 s60, s19, -1
	v_lshl_or_b32 v0, v1, 6, v0
	s_add_i32 s61, 0, 0x10000
	s_add_i32 s62, 0, 0x14000
	s_sext_i32_i8 s63, s0
	v_mov_b32_e32 v137, v131
	v_lshl_add_u32 v138, v14, 1, v0
	v_mov_b32_e32 v139, v131
	v_mov_b64_e32 v[140:141], 0x800
	v_mov_b64_e32 v[142:143], 0x7ff
	v_add_u32_e32 v153, s61, v151
	v_add_u32_e32 v154, s62, v151
	v_add_u32_e32 v155, 0, v3
	s_barrier
	v_readlane_b32 s17, v254, 8
	v_readlane_b32 s20, v254, 11
	v_readlane_b32 s21, v254, 12
	v_readlane_b32 s22, v254, 13
	v_readlane_b32 s23, v254, 14
	v_readlane_b32 s24, v254, 15
	v_readlane_b32 s25, v254, 16
	v_readlane_b32 s26, v254, 17
	v_readlane_b32 s27, v254, 18
	v_readlane_b32 s28, v254, 19
	v_readlane_b32 s29, v254, 20
	v_readlane_b32 s30, v254, 21
	v_readlane_b32 s31, v254, 22
	s_branch .LBB0_751

.Lmy_prio_skip4:
.LBB0_758:
	ds_read_b128 v[144:147], v153
	ds_read_b128 v[156:159], v153 offset:1024
	ds_read_b128 v[160:163], v153 offset:2048
	ds_read_b128 v[164:167], v153 offset:3072
	ds_read_b128 v[168:171], v154
	ds_read_b128 v[172:175], v154 offset:1024
	ds_read_b128 v[176:179], v154 offset:2048
	ds_read_b128 v[180:183], v154 offset:3072
	s_add_u32 s37, s38, 0xfff00080
	s_addc_u32 s40, s39, -1
	s_cmp_eq_u32 s36, 60
	s_cselect_b32 s49, s13, s40
	s_cselect_b32 s48, s64, s37
	s_cselect_b32 s47, s11, s35
	s_cselect_b32 s46, s65, s34
	s_add_i32 m0, s76, 0xc000
	ds_read_b128 v[184:187], v155
	ds_read_b128 v[188:191], v155 offset:1024
	ds_read_b128 v[192:195], v155 offset:2048
	ds_read_b128 v[196:199], v155 offset:3072
	ds_read_b128 v[200:203], v155 offset:4096
	ds_read_b128 v[204:207], v155 offset:5120
	ds_read_b128 v[208:211], v155 offset:6144
	ds_read_b128 v[212:215], v155 offset:7168
	global_load_lds_dwordx4 v136, s[38:39]
	s_add_i32 m0, s76, 0xe000
	s_nop 0
	global_load_lds_dwordx4 v138, s[38:39]
	s_waitcnt vmcnt(8)
	s_waitcnt lgkmcnt(0)
	s_barrier
	s_waitcnt lgkmcnt(0)
	v_mfma_f32_16x16x32_bf16 v[124:127], v[144:147], v[184:187], v[124:127]
	v_mfma_f32_16x16x32_bf16 v[120:123], v[160:163], v[184:187], v[120:123]
	v_mfma_f32_16x16x32_bf16 v[108:111], v[144:147], v[192:195], v[108:111]
	v_mfma_f32_16x16x32_bf16 v[104:107], v[160:163], v[192:195], v[104:107]
	v_mfma_f32_16x16x32_bf16 v[92:95], v[144:147], v[200:203], v[92:95]
	v_mfma_f32_16x16x32_bf16 v[88:91], v[160:163], v[200:203], v[88:91]
	v_mfma_f32_16x16x32_bf16 v[76:79], v[144:147], v[208:211], v[76:79]
	v_mfma_f32_16x16x32_bf16 v[72:75], v[160:163], v[208:211], v[72:75]
	v_mfma_f32_16x16x32_bf16 v[124:127], v[156:159], v[188:191], v[124:127]
	v_mfma_f32_16x16x32_bf16 v[120:123], v[164:167], v[188:191], v[120:123]
	v_mfma_f32_16x16x32_bf16 v[108:111], v[156:159], v[196:199], v[108:111]
	v_mfma_f32_16x16x32_bf16 v[104:107], v[164:167], v[196:199], v[104:107]
	v_mfma_f32_16x16x32_bf16 v[92:95], v[156:159], v[204:207], v[92:95]
	v_mfma_f32_16x16x32_bf16 v[88:91], v[164:167], v[204:207], v[88:91]
	v_mfma_f32_16x16x32_bf16 v[76:79], v[156:159], v[212:215], v[76:79]
	v_mfma_f32_16x16x32_bf16 v[72:75], v[164:167], v[212:215], v[72:75]
	v_mfma_f32_16x16x32_bf16 v[116:119], v[168:171], v[184:187], v[116:119]
	v_mfma_f32_16x16x32_bf16 v[112:115], v[176:179], v[184:187], v[112:115]
	v_mfma_f32_16x16x32_bf16 v[100:103], v[168:171], v[192:195], v[100:103]
	v_mfma_f32_16x16x32_bf16 v[96:99], v[176:179], v[192:195], v[96:99]
	v_mfma_f32_16x16x32_bf16 v[84:87], v[168:171], v[200:203], v[84:87]
	v_mfma_f32_16x16x32_bf16 v[80:83], v[176:179], v[200:203], v[80:83]
	v_mfma_f32_16x16x32_bf16 v[68:71], v[168:171], v[208:211], v[68:71]
	v_mfma_f32_16x16x32_bf16 v[64:67], v[176:179], v[208:211], v[64:67]
	v_mfma_f32_16x16x32_bf16 v[116:119], v[172:175], v[188:191], v[116:119]
	v_mfma_f32_16x16x32_bf16 v[112:115], v[180:183], v[188:191], v[112:115]
	v_mfma_f32_16x16x32_bf16 v[100:103], v[172:175], v[196:199], v[100:103]
	v_mfma_f32_16x16x32_bf16 v[96:99], v[180:183], v[196:199], v[96:99]
	v_mfma_f32_16x16x32_bf16 v[84:87], v[172:175], v[204:207], v[84:87]
	v_mfma_f32_16x16x32_bf16 v[80:83], v[180:183], v[204:207], v[80:83]
	v_mfma_f32_16x16x32_bf16 v[68:71], v[172:175], v[212:215], v[68:71]
	v_mfma_f32_16x16x32_bf16 v[64:67], v[180:183], v[212:215], v[64:67]
	s_barrier
	s_add_i32 s37, s61, s67
	s_mov_b32 m0, s37
	ds_read_b128 v[184:187], v155 offset:16384
	ds_read_b128 v[188:191], v155 offset:17408
	ds_read_b128 v[192:195], v155 offset:18432
	ds_read_b128 v[196:199], v155 offset:19456
	ds_read_b128 v[200:203], v155 offset:20480
	ds_read_b128 v[204:207], v155 offset:21504
	ds_read_b128 v[208:211], v155 offset:22528
	ds_read_b128 v[212:215], v155 offset:23552
	global_load_lds_dwordx4 v130, s[46:47]
	s_add_i32 m0, s37, 0x2000
	s_add_u32 s40, s46, 0x40000
	s_addc_u32 s41, s47, 0
	s_add_i32 s37, s62, s67
	global_load_lds_dwordx4 v134, s[46:47]
	s_mov_b32 m0, s37
	global_load_lds_dwordx4 v130, s[40:41]
	s_add_i32 m0, s37, 0x2000
	s_nop 0
	global_load_lds_dwordx4 v134, s[40:41]
	s_mov_b32 m0, s76
	s_nop 0
	global_load_lds_dwordx4 v128, s[48:49]
	s_mov_b32 m0, s52
	s_nop 0
	global_load_lds_dwordx4 v132, s[48:49]
	s_waitcnt vmcnt(8)
	s_waitcnt lgkmcnt(0)
	s_barrier
	s_waitcnt lgkmcnt(0)
	v_mfma_f32_16x16x32_bf16 v[60:63], v[144:147], v[184:187], v[60:63]
	v_mfma_f32_16x16x32_bf16 v[56:59], v[160:163], v[184:187], v[56:59]
	v_mfma_f32_16x16x32_bf16 v[44:47], v[144:147], v[192:195], v[44:47]
	v_mfma_f32_16x16x32_bf16 v[40:43], v[160:163], v[192:195], v[40:43]
	v_mfma_f32_16x16x32_bf16 v[28:31], v[144:147], v[200:203], v[28:31]
	v_mfma_f32_16x16x32_bf16 v[24:27], v[160:163], v[200:203], v[24:27]
	v_mfma_f32_16x16x32_bf16 v[12:15], v[144:147], v[208:211], v[12:15]
	v_mfma_f32_16x16x32_bf16 v[8:11], v[160:163], v[208:211], v[8:11]
	v_mfma_f32_16x16x32_bf16 v[60:63], v[156:159], v[188:191], v[60:63]
	v_mfma_f32_16x16x32_bf16 v[56:59], v[164:167], v[188:191], v[56:59]
	v_mfma_f32_16x16x32_bf16 v[44:47], v[156:159], v[196:199], v[44:47]
	v_mfma_f32_16x16x32_bf16 v[40:43], v[164:167], v[196:199], v[40:43]
	v_mfma_f32_16x16x32_bf16 v[28:31], v[156:159], v[204:207], v[28:31]
	v_mfma_f32_16x16x32_bf16 v[24:27], v[164:167], v[204:207], v[24:27]
	v_mfma_f32_16x16x32_bf16 v[12:15], v[156:159], v[212:215], v[12:15]
	v_mfma_f32_16x16x32_bf16 v[8:11], v[164:167], v[212:215], v[8:11]
	v_mfma_f32_16x16x32_bf16 v[52:55], v[168:171], v[184:187], v[52:55]
	v_mfma_f32_16x16x32_bf16 v[48:51], v[176:179], v[184:187], v[48:51]
	v_mfma_f32_16x16x32_bf16 v[36:39], v[168:171], v[192:195], v[36:39]
	v_mfma_f32_16x16x32_bf16 v[32:35], v[176:179], v[192:195], v[32:35]
	v_mfma_f32_16x16x32_bf16 v[20:23], v[168:171], v[200:203], v[20:23]
	v_mfma_f32_16x16x32_bf16 v[16:19], v[176:179], v[200:203], v[16:19]
	v_mfma_f32_16x16x32_bf16 v[4:7], v[168:171], v[208:211], v[4:7]
	v_mfma_f32_16x16x32_bf16 v[0:3], v[176:179], v[208:211], v[0:3]
	v_mfma_f32_16x16x32_bf16 v[52:55], v[172:175], v[188:191], v[52:55]
	v_mfma_f32_16x16x32_bf16 v[48:51], v[180:183], v[188:191], v[48:51]
	v_mfma_f32_16x16x32_bf16 v[36:39], v[172:175], v[196:199], v[36:39]
	v_mfma_f32_16x16x32_bf16 v[32:35], v[180:183], v[196:199], v[32:35]
	v_mfma_f32_16x16x32_bf16 v[20:23], v[172:175], v[204:207], v[20:23]
	v_mfma_f32_16x16x32_bf16 v[16:19], v[180:183], v[204:207], v[16:19]
	v_mfma_f32_16x16x32_bf16 v[4:7], v[172:175], v[212:215], v[4:7]
	v_mfma_f32_16x16x32_bf16 v[0:3], v[180:183], v[212:215], v[0:3]
	s_barrier
	s_add_i32 s37, 0, 0x18000
	s_add_i32 s42, 0, 0x1c000
	v_add_u32_e32 v164, s37, v151
	v_add_u32_e32 v180, s42, v151
	ds_read_b128 v[144:147], v164
	ds_read_b128 v[156:159], v164 offset:1024
	ds_read_b128 v[160:163], v164 offset:2048
	ds_read_b128 v[164:167], v164 offset:3072
	ds_read_b128 v[168:171], v180
	ds_read_b128 v[172:175], v180 offset:1024
	ds_read_b128 v[176:179], v180 offset:2048
	ds_read_b128 v[180:183], v180 offset:3072
	s_add_u32 s40, s48, 0x100000
	s_addc_u32 s41, s49, 0
	s_mov_b32 m0, s53
	ds_read_b128 v[184:187], v155 offset:32768
	ds_read_b128 v[188:191], v155 offset:33792
	ds_read_b128 v[192:195], v155 offset:34816
	ds_read_b128 v[196:199], v155 offset:35840
	ds_read_b128 v[200:203], v155 offset:36864
	ds_read_b128 v[204:207], v155 offset:37888
	ds_read_b128 v[208:211], v155 offset:38912
	ds_read_b128 v[212:215], v155 offset:39936
	global_load_lds_dwordx4 v128, s[40:41]
	s_mov_b32 m0, s54
	s_nop 0
	global_load_lds_dwordx4 v132, s[40:41]
	s_waitcnt vmcnt(8)
	s_waitcnt lgkmcnt(0)
	s_barrier
	s_waitcnt lgkmcnt(0)
	v_mfma_f32_16x16x32_bf16 v[124:127], v[144:147], v[184:187], v[124:127]
	v_mfma_f32_16x16x32_bf16 v[120:123], v[160:163], v[184:187], v[120:123]
	v_mfma_f32_16x16x32_bf16 v[108:111], v[144:147], v[192:195], v[108:111]
	v_mfma_f32_16x16x32_bf16 v[104:107], v[160:163], v[192:195], v[104:107]
	v_mfma_f32_16x16x32_bf16 v[92:95], v[144:147], v[200:203], v[92:95]
	v_mfma_f32_16x16x32_bf16 v[88:91], v[160:163], v[200:203], v[88:91]
	v_mfma_f32_16x16x32_bf16 v[76:79], v[144:147], v[208:211], v[76:79]
	v_mfma_f32_16x16x32_bf16 v[72:75], v[160:163], v[208:211], v[72:75]
	v_mfma_f32_16x16x32_bf16 v[124:127], v[156:159], v[188:191], v[124:127]
	v_mfma_f32_16x16x32_bf16 v[120:123], v[164:167], v[188:191], v[120:123]
	v_mfma_f32_16x16x32_bf16 v[108:111], v[156:159], v[196:199], v[108:111]
	v_mfma_f32_16x16x32_bf16 v[104:107], v[164:167], v[196:199], v[104:107]
	v_mfma_f32_16x16x32_bf16 v[92:95], v[156:159], v[204:207], v[92:95]
	v_mfma_f32_16x16x32_bf16 v[88:91], v[164:167], v[204:207], v[88:91]
	v_mfma_f32_16x16x32_bf16 v[76:79], v[156:159], v[212:215], v[76:79]
	v_mfma_f32_16x16x32_bf16 v[72:75], v[164:167], v[212:215], v[72:75]
	v_mfma_f32_16x16x32_bf16 v[116:119], v[168:171], v[184:187], v[116:119]
	v_mfma_f32_16x16x32_bf16 v[112:115], v[176:179], v[184:187], v[112:115]
	v_mfma_f32_16x16x32_bf16 v[100:103], v[168:171], v[192:195], v[100:103]
	v_mfma_f32_16x16x32_bf16 v[96:99], v[176:179], v[192:195], v[96:99]
	v_mfma_f32_16x16x32_bf16 v[84:87], v[168:171], v[200:203], v[84:87]
	v_mfma_f32_16x16x32_bf16 v[80:83], v[176:179], v[200:203], v[80:83]
	v_mfma_f32_16x16x32_bf16 v[68:71], v[168:171], v[208:211], v[68:71]
	v_mfma_f32_16x16x32_bf16 v[64:67], v[176:179], v[208:211], v[64:67]
	v_mfma_f32_16x16x32_bf16 v[116:119], v[172:175], v[188:191], v[116:119]
	v_mfma_f32_16x16x32_bf16 v[112:115], v[180:183], v[188:191], v[112:115]
	v_mfma_f32_16x16x32_bf16 v[100:103], v[172:175], v[196:199], v[100:103]
	v_mfma_f32_16x16x32_bf16 v[96:99], v[180:183], v[196:199], v[96:99]
	v_mfma_f32_16x16x32_bf16 v[84:87], v[172:175], v[204:207], v[84:87]
	v_mfma_f32_16x16x32_bf16 v[80:83], v[180:183], v[204:207], v[80:83]
	v_mfma_f32_16x16x32_bf16 v[68:71], v[172:175], v[212:215], v[68:71]
	v_mfma_f32_16x16x32_bf16 v[64:67], v[180:183], v[212:215], v[64:67]
	s_barrier
	s_add_i32 s37, s37, s67
	s_mov_b32 m0, s37
	ds_read_b128 v[184:187], v155 offset:49152
	ds_read_b128 v[188:191], v155 offset:50176
	ds_read_b128 v[192:195], v155 offset:51200
	ds_read_b128 v[196:199], v155 offset:52224
	ds_read_b128 v[200:203], v155 offset:53248
	ds_read_b128 v[204:207], v155 offset:54272
	ds_read_b128 v[208:211], v155 offset:55296
	ds_read_b128 v[212:215], v155 offset:56320
	s_add_u32 s100, s46, 0x80
	s_addc_u32 s101, s47, 0
	global_load_lds_dwordx4 v130, s[100:101]
	s_add_i32 m0, s37, 0x2000
	s_add_u32 s40, s46, 0x40080
	s_addc_u32 s41, s47, 0
	s_add_i32 s37, s42, s67
	s_add_u32 s100, s46, 0x80
	s_addc_u32 s101, s47, 0
	global_load_lds_dwordx4 v134, s[100:101]
	s_mov_b32 m0, s37
	s_nop 0
	global_load_lds_dwordx4 v130, s[40:41]
	s_add_i32 m0, s37, 0x2000
	s_nop 0
	global_load_lds_dwordx4 v134, s[40:41]
	s_mov_b32 m0, s56
	s_nop 0
	s_add_u32 s100, s48, 0x80
	s_addc_u32 s101, s49, 0
	global_load_lds_dwordx4 v128, s[100:101]
	s_mov_b32 m0, s57
	s_nop 0
	s_add_u32 s100, s48, 0x80
	s_addc_u32 s101, s49, 0
	global_load_lds_dwordx4 v132, s[100:101]
	s_waitcnt vmcnt(8)
	s_waitcnt lgkmcnt(0)
	s_barrier
	s_waitcnt lgkmcnt(0)
	v_mfma_f32_16x16x32_bf16 v[60:63], v[144:147], v[184:187], v[60:63]
	v_mfma_f32_16x16x32_bf16 v[56:59], v[160:163], v[184:187], v[56:59]
	v_mfma_f32_16x16x32_bf16 v[44:47], v[144:147], v[192:195], v[44:47]
	v_mfma_f32_16x16x32_bf16 v[40:43], v[160:163], v[192:195], v[40:43]
	v_mfma_f32_16x16x32_bf16 v[28:31], v[144:147], v[200:203], v[28:31]
	v_mfma_f32_16x16x32_bf16 v[24:27], v[160:163], v[200:203], v[24:27]
	v_mfma_f32_16x16x32_bf16 v[12:15], v[144:147], v[208:211], v[12:15]
	v_mfma_f32_16x16x32_bf16 v[8:11], v[160:163], v[208:211], v[8:11]
	v_mfma_f32_16x16x32_bf16 v[60:63], v[156:159], v[188:191], v[60:63]
	v_mfma_f32_16x16x32_bf16 v[56:59], v[164:167], v[188:191], v[56:59]
	v_mfma_f32_16x16x32_bf16 v[44:47], v[156:159], v[196:199], v[44:47]
	v_mfma_f32_16x16x32_bf16 v[40:43], v[164:167], v[196:199], v[40:43]
	v_mfma_f32_16x16x32_bf16 v[28:31], v[156:159], v[204:207], v[28:31]
	v_mfma_f32_16x16x32_bf16 v[24:27], v[164:167], v[204:207], v[24:27]
	v_mfma_f32_16x16x32_bf16 v[12:15], v[156:159], v[212:215], v[12:15]
	v_mfma_f32_16x16x32_bf16 v[8:11], v[164:167], v[212:215], v[8:11]
	v_mfma_f32_16x16x32_bf16 v[52:55], v[168:171], v[184:187], v[52:55]
	v_mfma_f32_16x16x32_bf16 v[48:51], v[176:179], v[184:187], v[48:51]
	v_mfma_f32_16x16x32_bf16 v[36:39], v[168:171], v[192:195], v[36:39]
	v_mfma_f32_16x16x32_bf16 v[32:35], v[176:179], v[192:195], v[32:35]
	v_mfma_f32_16x16x32_bf16 v[20:23], v[168:171], v[200:203], v[20:23]
	v_mfma_f32_16x16x32_bf16 v[16:19], v[176:179], v[200:203], v[16:19]
	v_mfma_f32_16x16x32_bf16 v[4:7], v[168:171], v[208:211], v[4:7]
	v_mfma_f32_16x16x32_bf16 v[0:3], v[176:179], v[208:211], v[0:3]
	v_mfma_f32_16x16x32_bf16 v[52:55], v[172:175], v[188:191], v[52:55]
	v_mfma_f32_16x16x32_bf16 v[48:51], v[180:183], v[188:191], v[48:51]
	v_mfma_f32_16x16x32_bf16 v[36:39], v[172:175], v[196:199], v[36:39]
	v_mfma_f32_16x16x32_bf16 v[32:35], v[180:183], v[196:199], v[32:35]
	v_mfma_f32_16x16x32_bf16 v[20:23], v[172:175], v[204:207], v[20:23]
	v_mfma_f32_16x16x32_bf16 v[16:19], v[180:183], v[204:207], v[16:19]
	v_mfma_f32_16x16x32_bf16 v[4:7], v[172:175], v[212:215], v[4:7]
	v_mfma_f32_16x16x32_bf16 v[0:3], v[180:183], v[212:215], v[0:3]
	s_barrier
	s_add_i32 s36, s36, 2
	s_add_u32 s38, s38, 0x100
	s_addc_u32 s39, s39, 0
	s_add_u32 s34, s34, 0x100
	s_addc_u32 s35, s35, 0
	s_cmp_gt_u32 s36, 61
	s_cbranch_scc0 .LBB0_758
	s_setprio 0
	s_and_b64 vcc, exec, s[8:9]
	s_cbranch_vccz .LBB0_761
	s_barrier
.LBB0_761:
	v_lshl_add_u32 v148, s44, 8, v150
	v_and_b32_e32 v146, 0x60, v152
	v_add_u32_e32 v146, v146, v152
	v_lshl_or_b32 v146, s63, 8, v146
	s_cmp_lt_i32 s44, 64
	v_readlane_b32 s36, v254, 7
	v_readlane_b32 s37, v254, 8
	v_readlane_b32 s38, v254, 9
	v_readlane_b32 s39, v254, 10
	s_cselect_b32 s39, s37, s60
	s_cselect_b32 s38, s36, s59
	v_and_b32_e32 v149, 0xfffffff7, v150
	v_lshl_add_u32 v149, s44, 8, v149
	v_bfe_u32 v147, v150, 3, 1
	v_lshlrev_b32_e32 v149, 13, v149
	v_lshl_add_u32 v149, v146, 1, v149
	v_lshl_add_u32 v149, v147, 6, v149
	v_lshlrev_b32_e32 v148, 14, v148
	v_lshl_add_u32 v148, v146, 2, v148
	s_add_u32 s100, s38, 0x0
	s_addc_u32 s101, s39, 0
	global_load_dwordx4 v[144:147], v148, s[100:101]
	global_load_dwordx4 v[156:159], v148, s[100:101] offset:16
	global_load_dwordx4 v[160:163], v148, s[100:101] offset:128
	global_load_dwordx4 v[164:167], v148, s[100:101] offset:144
	s_add_u32 s100, s38, 0x40000
	s_addc_u32 s101, s39, 0
	global_load_dwordx4 v[168:171], v148, s[100:101]
	global_load_dwordx4 v[172:175], v148, s[100:101] offset:16
	global_load_dwordx4 v[176:179], v148, s[100:101] offset:128
	global_load_dwordx4 v[180:183], v148, s[100:101] offset:144
	s_add_u32 s100, s38, 0x80000
	s_addc_u32 s101, s39, 0
	global_load_dwordx4 v[184:187], v148, s[100:101]
	global_load_dwordx4 v[188:191], v148, s[100:101] offset:16
	global_load_dwordx4 v[192:195], v148, s[100:101] offset:128
	global_load_dwordx4 v[196:199], v148, s[100:101] offset:144
	s_add_u32 s100, s38, 0xc0000
	s_addc_u32 s101, s39, 0
	global_load_dwordx4 v[200:203], v148, s[100:101]
	global_load_dwordx4 v[204:207], v148, s[100:101] offset:16
	global_load_dwordx4 v[208:211], v148, s[100:101] offset:128
	global_load_dwordx4 v[212:215], v148, s[100:101] offset:144
	v_readlane_b32 s40, v254, 11
	v_readlane_b32 s41, v254, 12
	v_readlane_b32 s42, v254, 13
	v_readlane_b32 s43, v254, 14
	v_readlane_b32 s44, v254, 15
	v_readlane_b32 s45, v254, 16
	v_readlane_b32 s46, v254, 17
	v_readlane_b32 s47, v254, 18
	v_readlane_b32 s48, v254, 19
	v_readlane_b32 s49, v254, 20
	v_readlane_b32 s50, v254, 21
	v_readlane_b32 s51, v254, 22
	s_waitcnt vmcnt(12)
	v_pk_add_f32 v[124:125], v[124:125], v[144:145]
	v_pk_add_f32 v[126:127], v[126:127], v[146:147]
	v_pk_add_f32 v[120:121], v[120:121], v[156:157]
	v_pk_add_f32 v[122:123], v[122:123], v[158:159]
	v_pk_add_f32 v[116:117], v[116:117], v[160:161]
	v_pk_add_f32 v[118:119], v[118:119], v[162:163]
	v_pk_add_f32 v[112:113], v[112:113], v[164:165]
	v_pk_add_f32 v[114:115], v[114:115], v[166:167]
	v_cvt_pk_bf16_f32 v124, v124, v125
	v_cvt_pk_bf16_f32 v125, v126, v127
	v_cvt_pk_bf16_f32 v126, v120, v121
	v_cvt_pk_bf16_f32 v127, v122, v123
	v_cvt_pk_bf16_f32 v116, v116, v117
	v_cvt_pk_bf16_f32 v117, v118, v119
	v_cvt_pk_bf16_f32 v118, v112, v113
	v_cvt_pk_bf16_f32 v119, v114, v115
	s_add_u32 vcc_lo, s74, 0x0
	s_addc_u32 vcc_hi, s75, 0
	v_mov_b32_dpp v120, v124 row_ror:8 row_mask:0xf bank_mask:0xf
	v_mov_b32_dpp v121, v125 row_ror:8 row_mask:0xf bank_mask:0xf
	v_mov_b32_dpp v122, v126 row_ror:8 row_mask:0xf bank_mask:0xf
	v_mov_b32_dpp v123, v127 row_ror:8 row_mask:0xf bank_mask:0xf
	v_mov_b32_dpp v124, v116 row_ror:8 row_mask:0xf bank_mask:0xc
	v_mov_b32_dpp v125, v117 row_ror:8 row_mask:0xf bank_mask:0xc
	v_mov_b32_dpp v126, v118 row_ror:8 row_mask:0xf bank_mask:0xc
	v_mov_b32_dpp v127, v119 row_ror:8 row_mask:0xf bank_mask:0xc
	v_mov_b32_dpp v116, v120 quad_perm:[0,1,2,3] row_mask:0xf bank_mask:0x3
	v_mov_b32_dpp v117, v121 quad_perm:[0,1,2,3] row_mask:0xf bank_mask:0x3
	v_mov_b32_dpp v118, v122 quad_perm:[0,1,2,3] row_mask:0xf bank_mask:0x3
	v_mov_b32_dpp v119, v123 quad_perm:[0,1,2,3] row_mask:0xf bank_mask:0x3
	global_store_dwordx4 v149, v[124:127], vcc
	s_add_u32 vcc_lo, vcc_lo, 0x10000
	s_addc_u32 vcc_hi, vcc_hi, 0
	global_store_dwordx4 v149, v[116:119], vcc
	s_add_u32 s100, s38, 0x200000
	s_addc_u32 s101, s39, 0
	global_load_dwordx4 v[144:147], v148, s[100:101]
	global_load_dwordx4 v[156:159], v148, s[100:101] offset:16
	global_load_dwordx4 v[160:163], v148, s[100:101] offset:128
	global_load_dwordx4 v[164:167], v148, s[100:101] offset:144
	s_waitcnt vmcnt(14)
	v_pk_add_f32 v[108:109], v[108:109], v[168:169]
	v_pk_add_f32 v[110:111], v[110:111], v[170:171]
	v_pk_add_f32 v[104:105], v[104:105], v[172:173]
	v_pk_add_f32 v[106:107], v[106:107], v[174:175]
	v_pk_add_f32 v[100:101], v[100:101], v[176:177]
	v_pk_add_f32 v[102:103], v[102:103], v[178:179]
	v_pk_add_f32 v[96:97], v[96:97], v[180:181]
	v_pk_add_f32 v[98:99], v[98:99], v[182:183]
	v_cvt_pk_bf16_f32 v108, v108, v109
	v_cvt_pk_bf16_f32 v109, v110, v111
	v_cvt_pk_bf16_f32 v110, v104, v105
	v_cvt_pk_bf16_f32 v111, v106, v107
	v_cvt_pk_bf16_f32 v100, v100, v101
	v_cvt_pk_bf16_f32 v101, v102, v103
	v_cvt_pk_bf16_f32 v102, v96, v97
	v_cvt_pk_bf16_f32 v103, v98, v99
	s_add_u32 vcc_lo, s74, 0x20000
	s_addc_u32 vcc_hi, s75, 0
	v_mov_b32_dpp v104, v108 row_ror:8 row_mask:0xf bank_mask:0xf
	v_mov_b32_dpp v105, v109 row_ror:8 row_mask:0xf bank_mask:0xf
	v_mov_b32_dpp v106, v110 row_ror:8 row_mask:0xf bank_mask:0xf
	v_mov_b32_dpp v107, v111 row_ror:8 row_mask:0xf bank_mask:0xf
	v_mov_b32_dpp v108, v100 row_ror:8 row_mask:0xf bank_mask:0xc
	v_mov_b32_dpp v109, v101 row_ror:8 row_mask:0xf bank_mask:0xc
	v_mov_b32_dpp v110, v102 row_ror:8 row_mask:0xf bank_mask:0xc
	v_mov_b32_dpp v111, v103 row_ror:8 row_mask:0xf bank_mask:0xc
	v_mov_b32_dpp v100, v104 quad_perm:[0,1,2,3] row_mask:0xf bank_mask:0x3
	v_mov_b32_dpp v101, v105 quad_perm:[0,1,2,3] row_mask:0xf bank_mask:0x3
	v_mov_b32_dpp v102, v106 quad_perm:[0,1,2,3] row_mask:0xf bank_mask:0x3
	v_mov_b32_dpp v103, v107 quad_perm:[0,1,2,3] row_mask:0xf bank_mask:0x3
	global_store_dwordx4 v149, v[108:111], vcc
	s_add_u32 vcc_lo, vcc_lo, 0x10000
	s_addc_u32 vcc_hi, vcc_hi, 0
	global_store_dwordx4 v149, v[100:103], vcc
	s_add_u32 s100, s38, 0x240000
	s_addc_u32 s101, s39, 0
	global_load_dwordx4 v[168:171], v148, s[100:101]
	global_load_dwordx4 v[172:175], v148, s[100:101] offset:16
	global_load_dwordx4 v[176:179], v148, s[100:101] offset:128
	global_load_dwordx4 v[180:183], v148, s[100:101] offset:144
	s_waitcnt vmcnt(16)
	v_pk_add_f32 v[92:93], v[92:93], v[184:185]
	v_pk_add_f32 v[94:95], v[94:95], v[186:187]
	v_pk_add_f32 v[88:89], v[88:89], v[188:189]
	v_pk_add_f32 v[90:91], v[90:91], v[190:191]
	v_pk_add_f32 v[84:85], v[84:85], v[192:193]
	v_pk_add_f32 v[86:87], v[86:87], v[194:195]
	v_pk_add_f32 v[80:81], v[80:81], v[196:197]
	v_pk_add_f32 v[82:83], v[82:83], v[198:199]
	v_cvt_pk_bf16_f32 v92, v92, v93
	v_cvt_pk_bf16_f32 v93, v94, v95
	v_cvt_pk_bf16_f32 v94, v88, v89
	v_cvt_pk_bf16_f32 v95, v90, v91
	v_cvt_pk_bf16_f32 v84, v84, v85
	v_cvt_pk_bf16_f32 v85, v86, v87
	v_cvt_pk_bf16_f32 v86, v80, v81
	v_cvt_pk_bf16_f32 v87, v82, v83
	s_add_u32 vcc_lo, s74, 0x40000
	s_addc_u32 vcc_hi, s75, 0
	v_mov_b32_dpp v88, v92 row_ror:8 row_mask:0xf bank_mask:0xf
	v_mov_b32_dpp v89, v93 row_ror:8 row_mask:0xf bank_mask:0xf
	v_mov_b32_dpp v90, v94 row_ror:8 row_mask:0xf bank_mask:0xf
	v_mov_b32_dpp v91, v95 row_ror:8 row_mask:0xf bank_mask:0xf
	v_mov_b32_dpp v92, v84 row_ror:8 row_mask:0xf bank_mask:0xc
	v_mov_b32_dpp v93, v85 row_ror:8 row_mask:0xf bank_mask:0xc
	v_mov_b32_dpp v94, v86 row_ror:8 row_mask:0xf bank_mask:0xc
	v_mov_b32_dpp v95, v87 row_ror:8 row_mask:0xf bank_mask:0xc
	v_mov_b32_dpp v84, v88 quad_perm:[0,1,2,3] row_mask:0xf bank_mask:0x3
	v_mov_b32_dpp v85, v89 quad_perm:[0,1,2,3] row_mask:0xf bank_mask:0x3
	v_mov_b32_dpp v86, v90 quad_perm:[0,1,2,3] row_mask:0xf bank_mask:0x3
	v_mov_b32_dpp v87, v91 quad_perm:[0,1,2,3] row_mask:0xf bank_mask:0x3
	global_store_dwordx4 v149, v[92:95], vcc
	s_add_u32 vcc_lo, vcc_lo, 0x10000
	s_addc_u32 vcc_hi, vcc_hi, 0
	global_store_dwordx4 v149, v[84:87], vcc
	s_add_u32 s100, s38, 0x280000
	s_addc_u32 s101, s39, 0
	global_load_dwordx4 v[184:187], v148, s[100:101]
	global_load_dwordx4 v[188:191], v148, s[100:101] offset:16
	global_load_dwordx4 v[192:195], v148, s[100:101] offset:128
	global_load_dwordx4 v[196:199], v148, s[100:101] offset:144
	s_waitcnt vmcnt(18)
	v_pk_add_f32 v[76:77], v[76:77], v[200:201]
	v_pk_add_f32 v[78:79], v[78:79], v[202:203]
	v_pk_add_f32 v[72:73], v[72:73], v[204:205]
	v_pk_add_f32 v[74:75], v[74:75], v[206:207]
	v_pk_add_f32 v[68:69], v[68:69], v[208:209]
	v_pk_add_f32 v[70:71], v[70:71], v[210:211]
	v_pk_add_f32 v[64:65], v[64:65], v[212:213]
	v_pk_add_f32 v[66:67], v[66:67], v[214:215]
	v_cvt_pk_bf16_f32 v76, v76, v77
	v_cvt_pk_bf16_f32 v77, v78, v79
	v_cvt_pk_bf16_f32 v78, v72, v73
	v_cvt_pk_bf16_f32 v79, v74, v75
	v_cvt_pk_bf16_f32 v68, v68, v69
	v_cvt_pk_bf16_f32 v69, v70, v71
	v_cvt_pk_bf16_f32 v70, v64, v65
	v_cvt_pk_bf16_f32 v71, v66, v67
	s_add_u32 vcc_lo, s74, 0x60000
	s_addc_u32 vcc_hi, s75, 0
	v_mov_b32_dpp v72, v76 row_ror:8 row_mask:0xf bank_mask:0xf
	v_mov_b32_dpp v73, v77 row_ror:8 row_mask:0xf bank_mask:0xf
	v_mov_b32_dpp v74, v78 row_ror:8 row_mask:0xf bank_mask:0xf
	v_mov_b32_dpp v75, v79 row_ror:8 row_mask:0xf bank_mask:0xf
	v_mov_b32_dpp v76, v68 row_ror:8 row_mask:0xf bank_mask:0xc
	v_mov_b32_dpp v77, v69 row_ror:8 row_mask:0xf bank_mask:0xc
	v_mov_b32_dpp v78, v70 row_ror:8 row_mask:0xf bank_mask:0xc
	v_mov_b32_dpp v79, v71 row_ror:8 row_mask:0xf bank_mask:0xc
	v_mov_b32_dpp v68, v72 quad_perm:[0,1,2,3] row_mask:0xf bank_mask:0x3
	v_mov_b32_dpp v69, v73 quad_perm:[0,1,2,3] row_mask:0xf bank_mask:0x3
	v_mov_b32_dpp v70, v74 quad_perm:[0,1,2,3] row_mask:0xf bank_mask:0x3
	v_mov_b32_dpp v71, v75 quad_perm:[0,1,2,3] row_mask:0xf bank_mask:0x3
	global_store_dwordx4 v149, v[76:79], vcc
	s_add_u32 vcc_lo, vcc_lo, 0x10000
	s_addc_u32 vcc_hi, vcc_hi, 0
	global_store_dwordx4 v149, v[68:71], vcc
	s_add_u32 s100, s38, 0x2c0000
	s_addc_u32 s101, s39, 0
	global_load_dwordx4 v[200:203], v148, s[100:101]
	global_load_dwordx4 v[204:207], v148, s[100:101] offset:16
	global_load_dwordx4 v[208:211], v148, s[100:101] offset:128
	global_load_dwordx4 v[212:215], v148, s[100:101] offset:144
	s_waitcnt vmcnt(18)
	v_pk_add_f32 v[60:61], v[60:61], v[144:145]
	v_pk_add_f32 v[62:63], v[62:63], v[146:147]
	v_pk_add_f32 v[56:57], v[56:57], v[156:157]
	v_pk_add_f32 v[58:59], v[58:59], v[158:159]
	v_pk_add_f32 v[52:53], v[52:53], v[160:161]
	v_pk_add_f32 v[54:55], v[54:55], v[162:163]
	v_pk_add_f32 v[48:49], v[48:49], v[164:165]
	v_pk_add_f32 v[50:51], v[50:51], v[166:167]
	v_cvt_pk_bf16_f32 v60, v60, v61
	v_cvt_pk_bf16_f32 v61, v62, v63
	v_cvt_pk_bf16_f32 v62, v56, v57
	v_cvt_pk_bf16_f32 v63, v58, v59
	v_cvt_pk_bf16_f32 v52, v52, v53
	v_cvt_pk_bf16_f32 v53, v54, v55
	v_cvt_pk_bf16_f32 v54, v48, v49
	v_cvt_pk_bf16_f32 v55, v50, v51
	s_add_u32 vcc_lo, s74, 0x100000
	s_addc_u32 vcc_hi, s75, 0
	v_mov_b32_dpp v56, v60 row_ror:8 row_mask:0xf bank_mask:0xf
	v_mov_b32_dpp v57, v61 row_ror:8 row_mask:0xf bank_mask:0xf
	v_mov_b32_dpp v58, v62 row_ror:8 row_mask:0xf bank_mask:0xf
	v_mov_b32_dpp v59, v63 row_ror:8 row_mask:0xf bank_mask:0xf
	v_mov_b32_dpp v60, v52 row_ror:8 row_mask:0xf bank_mask:0xc
	v_mov_b32_dpp v61, v53 row_ror:8 row_mask:0xf bank_mask:0xc
	v_mov_b32_dpp v62, v54 row_ror:8 row_mask:0xf bank_mask:0xc
	v_mov_b32_dpp v63, v55 row_ror:8 row_mask:0xf bank_mask:0xc
	v_mov_b32_dpp v52, v56 quad_perm:[0,1,2,3] row_mask:0xf bank_mask:0x3
	v_mov_b32_dpp v53, v57 quad_perm:[0,1,2,3] row_mask:0xf bank_mask:0x3
	v_mov_b32_dpp v54, v58 quad_perm:[0,1,2,3] row_mask:0xf bank_mask:0x3
	v_mov_b32_dpp v55, v59 quad_perm:[0,1,2,3] row_mask:0xf bank_mask:0x3
	global_store_dwordx4 v149, v[60:63], vcc
	s_add_u32 vcc_lo, vcc_lo, 0x10000
	s_addc_u32 vcc_hi, vcc_hi, 0
	global_store_dwordx4 v149, v[52:55], vcc
	s_waitcnt vmcnt(14)
	v_pk_add_f32 v[44:45], v[44:45], v[168:169]
	v_pk_add_f32 v[46:47], v[46:47], v[170:171]
	v_pk_add_f32 v[40:41], v[40:41], v[172:173]
	v_pk_add_f32 v[42:43], v[42:43], v[174:175]
	v_pk_add_f32 v[36:37], v[36:37], v[176:177]
	v_pk_add_f32 v[38:39], v[38:39], v[178:179]
	v_pk_add_f32 v[32:33], v[32:33], v[180:181]
	v_pk_add_f32 v[34:35], v[34:35], v[182:183]
	v_cvt_pk_bf16_f32 v44, v44, v45
	v_cvt_pk_bf16_f32 v45, v46, v47
	v_cvt_pk_bf16_f32 v46, v40, v41
	v_cvt_pk_bf16_f32 v47, v42, v43
	v_cvt_pk_bf16_f32 v36, v36, v37
	v_cvt_pk_bf16_f32 v37, v38, v39
	v_cvt_pk_bf16_f32 v38, v32, v33
	v_cvt_pk_bf16_f32 v39, v34, v35
	s_add_u32 vcc_lo, s74, 0x120000
	s_addc_u32 vcc_hi, s75, 0
	v_mov_b32_dpp v40, v44 row_ror:8 row_mask:0xf bank_mask:0xf
	v_mov_b32_dpp v41, v45 row_ror:8 row_mask:0xf bank_mask:0xf
	v_mov_b32_dpp v42, v46 row_ror:8 row_mask:0xf bank_mask:0xf
	v_mov_b32_dpp v43, v47 row_ror:8 row_mask:0xf bank_mask:0xf
	v_mov_b32_dpp v44, v36 row_ror:8 row_mask:0xf bank_mask:0xc
	v_mov_b32_dpp v45, v37 row_ror:8 row_mask:0xf bank_mask:0xc
	v_mov_b32_dpp v46, v38 row_ror:8 row_mask:0xf bank_mask:0xc
	v_mov_b32_dpp v47, v39 row_ror:8 row_mask:0xf bank_mask:0xc
	v_mov_b32_dpp v36, v40 quad_perm:[0,1,2,3] row_mask:0xf bank_mask:0x3
	v_mov_b32_dpp v37, v41 quad_perm:[0,1,2,3] row_mask:0xf bank_mask:0x3
	v_mov_b32_dpp v38, v42 quad_perm:[0,1,2,3] row_mask:0xf bank_mask:0x3
	v_mov_b32_dpp v39, v43 quad_perm:[0,1,2,3] row_mask:0xf bank_mask:0x3
	global_store_dwordx4 v149, v[44:47], vcc
	s_add_u32 vcc_lo, vcc_lo, 0x10000
	s_addc_u32 vcc_hi, vcc_hi, 0
	global_store_dwordx4 v149, v[36:39], vcc
	s_waitcnt vmcnt(10)
	v_pk_add_f32 v[28:29], v[28:29], v[184:185]
	v_pk_add_f32 v[30:31], v[30:31], v[186:187]
	v_pk_add_f32 v[24:25], v[24:25], v[188:189]
	v_pk_add_f32 v[26:27], v[26:27], v[190:191]
	v_pk_add_f32 v[20:21], v[20:21], v[192:193]
	v_pk_add_f32 v[22:23], v[22:23], v[194:195]
	v_pk_add_f32 v[16:17], v[16:17], v[196:197]
	v_pk_add_f32 v[18:19], v[18:19], v[198:199]
	v_cvt_pk_bf16_f32 v28, v28, v29
	v_cvt_pk_bf16_f32 v29, v30, v31
	v_cvt_pk_bf16_f32 v30, v24, v25
	v_cvt_pk_bf16_f32 v31, v26, v27
	v_cvt_pk_bf16_f32 v20, v20, v21
	v_cvt_pk_bf16_f32 v21, v22, v23
	v_cvt_pk_bf16_f32 v22, v16, v17
	v_cvt_pk_bf16_f32 v23, v18, v19
	s_add_u32 vcc_lo, s74, 0x140000
	s_addc_u32 vcc_hi, s75, 0
	v_mov_b32_dpp v24, v28 row_ror:8 row_mask:0xf bank_mask:0xf
	v_mov_b32_dpp v25, v29 row_ror:8 row_mask:0xf bank_mask:0xf
	v_mov_b32_dpp v26, v30 row_ror:8 row_mask:0xf bank_mask:0xf
	v_mov_b32_dpp v27, v31 row_ror:8 row_mask:0xf bank_mask:0xf
	v_mov_b32_dpp v28, v20 row_ror:8 row_mask:0xf bank_mask:0xc
	v_mov_b32_dpp v29, v21 row_ror:8 row_mask:0xf bank_mask:0xc
	v_mov_b32_dpp v30, v22 row_ror:8 row_mask:0xf bank_mask:0xc
	v_mov_b32_dpp v31, v23 row_ror:8 row_mask:0xf bank_mask:0xc
	v_mov_b32_dpp v20, v24 quad_perm:[0,1,2,3] row_mask:0xf bank_mask:0x3
	v_mov_b32_dpp v21, v25 quad_perm:[0,1,2,3] row_mask:0xf bank_mask:0x3
	v_mov_b32_dpp v22, v26 quad_perm:[0,1,2,3] row_mask:0xf bank_mask:0x3
	v_mov_b32_dpp v23, v27 quad_perm:[0,1,2,3] row_mask:0xf bank_mask:0x3
	global_store_dwordx4 v149, v[28:31], vcc
	s_add_u32 vcc_lo, vcc_lo, 0x10000
	s_addc_u32 vcc_hi, vcc_hi, 0
	global_store_dwordx4 v149, v[20:23], vcc
	s_waitcnt vmcnt(6)
	v_pk_add_f32 v[12:13], v[12:13], v[200:201]
	v_pk_add_f32 v[14:15], v[14:15], v[202:203]
	v_pk_add_f32 v[8:9], v[8:9], v[204:205]
	v_pk_add_f32 v[10:11], v[10:11], v[206:207]
	v_pk_add_f32 v[4:5], v[4:5], v[208:209]
	v_pk_add_f32 v[6:7], v[6:7], v[210:211]
	v_pk_add_f32 v[0:1], v[0:1], v[212:213]
	v_pk_add_f32 v[2:3], v[2:3], v[214:215]
	v_cvt_pk_bf16_f32 v12, v12, v13
	v_cvt_pk_bf16_f32 v13, v14, v15
	v_cvt_pk_bf16_f32 v14, v8, v9
	v_cvt_pk_bf16_f32 v15, v10, v11
	v_cvt_pk_bf16_f32 v4, v4, v5
	v_cvt_pk_bf16_f32 v5, v6, v7
	v_cvt_pk_bf16_f32 v6, v0, v1
	v_cvt_pk_bf16_f32 v7, v2, v3
	s_add_u32 vcc_lo, s74, 0x160000
	s_addc_u32 vcc_hi, s75, 0
	v_mov_b32_dpp v8, v12 row_ror:8 row_mask:0xf bank_mask:0xf
	v_mov_b32_dpp v9, v13 row_ror:8 row_mask:0xf bank_mask:0xf
	v_mov_b32_dpp v10, v14 row_ror:8 row_mask:0xf bank_mask:0xf
	v_mov_b32_dpp v11, v15 row_ror:8 row_mask:0xf bank_mask:0xf
	v_mov_b32_dpp v12, v4 row_ror:8 row_mask:0xf bank_mask:0xc
	v_mov_b32_dpp v13, v5 row_ror:8 row_mask:0xf bank_mask:0xc
	v_mov_b32_dpp v14, v6 row_ror:8 row_mask:0xf bank_mask:0xc
	v_mov_b32_dpp v15, v7 row_ror:8 row_mask:0xf bank_mask:0xc
	v_mov_b32_dpp v4, v8 quad_perm:[0,1,2,3] row_mask:0xf bank_mask:0x3
	v_mov_b32_dpp v5, v9 quad_perm:[0,1,2,3] row_mask:0xf bank_mask:0x3
	v_mov_b32_dpp v6, v10 quad_perm:[0,1,2,3] row_mask:0xf bank_mask:0x3
	v_mov_b32_dpp v7, v11 quad_perm:[0,1,2,3] row_mask:0xf bank_mask:0x3
	global_store_dwordx4 v149, v[12:15], vcc
	s_add_u32 vcc_lo, vcc_lo, 0x10000
	s_addc_u32 vcc_hi, vcc_hi, 0
	global_store_dwordx4 v149, v[4:7], vcc
	s_andn2_b64 vcc, exec, s[0:1]
	s_mov_b64 s[0:1], -1
	s_cbranch_vccnz .LBB0_750
	s_andn2_b64 vcc, exec, s[4:5]
	s_cbranch_vccnz .LBB0_749
	s_barrier
	s_branch .LBB0_749
